# plus scan loaders: K^T and Att/T (Att/P15) fragment blocks copied as 16-byte pieces (5 fewer loads per loader step)
# baseline (speedup 1.0000x reference)
; #define LAS __attribute__((address_space(3)))
; __device__ __forceinline__ float bf1(bf16_t u) { return __uint_as_float(((unsigned)u) << 16); }
; __device__ __forceinline__ void scan_phase(const Params& P, int l, LAS unsigned char* lds) {
;     ...
;                         LAS unsigned char* sl = lds + (jw & 1) * SLOT + HGO;
; #pragma unroll
;                         for (int j = 0; j < 4; ++j) *(LAS u32x4*)(sl + (j * 64 + lane) * 16) = fq[j];
; #pragma unroll
;                         for (int m = 0; m < 8; ++m) *(LAS u32x2*)(sl + 4096 + (m * 64 + lane) * 8) = fk[m];
;                         *(LAS u32x2*)(sl + 8192 + lane * 8) = fa;
;                         if (lane < 32) *(LAS f32x4*)(sl + 8704 + lane * 16) = p15;
;                         *(LAS f32x4*)(sl + 9216 + lane * 16) = (f32x4){bf1(vr[0]), bf1(vr[1]), bf1(vr[2]), bf1(vr[3])};
;                     }
;                     if (jl < NT) {
;                         const int n0 = jl * TS; const int plo = dir ? (n0 < 256 ? 256 - TS - n0 : TPB + 256 - TS - n0) : n0;
;                         const size_t task = (size_t)grp * NCHUNK + jl;
;                         const unsigned char* cq = ws + WS_HGQ + task * 4096; const unsigned char* ck = ws + WS_HGK + task * 4096; const unsigned char* ca = ws + WS_HGA + task * 1024;
; #pragma unroll
;                         for (int j = 0; j < 4; ++j) fq[j] = *(const u32x4*)(cq + (size_t)(j * 64 + lane) * 16);
; #pragma unroll
;                         for (int m = 0; m < 8; ++m) fk[m] = *(const u32x2*)(ck + (size_t)(m * 64 + lane) * 8);
;                         fa = *(const u32x2*)(ca + (size_t)lane * 8);
;                         if (lane < 32) p15 = *(const f32x4*)(ca + 512 + (size_t)lane * 16);
.LBB0_681:
	s_mul_hi_u32 s14, s81, 0xaaaaaaab
	s_lshr_b32 s15, s14, 1
	s_mul_i32 s15, s15, 3
	s_sub_i32 s14, s27, s15
	s_add_i32 s14, s89, s14
	s_cmp_lg_u32 s14, -4
	s_cbranch_scc1 .LBB0_690
	s_cmp_lt_i32 s89, -1
	s_cselect_b64 s[20:21], -1, 0
	s_cmpk_eq_i32 s93, 0x1130
	s_cselect_b64 s[22:23], -1, 0
	s_or_b64 s[20:21], s[20:21], s[22:23]
	s_and_b64 vcc, exec, s[20:21]
	s_cbranch_vccnz .LBB0_686
	s_andn2_b32 s14, 1, s89
	s_mulk_i32 s14, 0x6500
	s_add_i32 s14, s14, 0
	v_add_u32_e32 v67, s14, v48
	v_add_u32_e32 v2, s14, v46
	v_add_u32_e32 v111, 0x100, v67
	s_waitcnt vmcnt(0)
	ds_write_b128 v2, v[16:19] offset:15616
	ds_write_b128 v2, v[12:15] offset:16640
	ds_write_b128 v2, v[8:11] offset:17664
	ds_write_b128 v2, v[4:7] offset:18688
	ds_write_b128 v2, v[176:179] offset:19712
	ds_write_b128 v2, v[180:183] offset:20736
	ds_write_b128 v2, v[184:187] offset:21760
	ds_write_b128 v2, v[188:191] offset:22784
	ds_write_b128 v2, v[192:195] offset:23808
	v_lshlrev_b32_e32 v112, 16, v47
	v_lshlrev_b32_e32 v113, 16, v68
	v_lshlrev_b32_e32 v114, 16, v69
	v_lshlrev_b32_e32 v115, 16, v70
	ds_write_b128 v2, v[112:115] offset:24832
.LBB0_686:
	s_cmpk_gt_i32 s89, 0x10b
	s_cbranch_scc1 .LBB0_690
	v_readlane_b32 s20, v252, 2
	v_readlane_b32 s21, v252, 3
	s_waitcnt vmcnt(4)
	s_nop 0
	v_lshl_add_u64 v[0:1], s[20:21], 0, v[30:31]
	v_add_co_u32_e32 v0, vcc, 0x2bd40000, v0
	s_nop 1
	v_addc_co_u32_e32 v1, vcc, 0, v1, vcc
	global_load_dwordx4 v[16:19], v[0:1], off
	global_load_dwordx4 v[12:15], v[0:1], off offset:1024
	global_load_dwordx4 v[8:11], v[0:1], off offset:2048
	global_load_dwordx4 v[4:7], v[0:1], off offset:3072
	v_lshl_add_u64 v[0:1], s[20:21], 0, v[32:33]
	v_add_co_u32_e32 v0, vcc, 0x41d60000, v0
	s_nop 1
	v_addc_co_u32_e32 v1, vcc, 0, v1, vcc
	v_add_co_u32_e32 v0, vcc, v48, v0
	s_nop 1
	v_addc_co_u32_e32 v1, vcc, 0, v1, vcc
	global_load_dwordx4 v[176:179], v[0:1], off
	global_load_dwordx4 v[180:183], v[0:1], off offset:1024
	global_load_dwordx4 v[184:187], v[0:1], off offset:2048
	global_load_dwordx4 v[188:191], v[0:1], off offset:3072
	v_lshl_add_u64 v[0:1], s[20:21], 0, v[26:27]
	v_add_co_u32_e32 v0, vcc, v48, v0
	s_nop 1
	v_addc_co_u32_e32 v1, vcc, 0, v1, vcc
	global_load_dwordx4 v[192:195], v[0:1], off
.LBB0_689:
	s_cmp_lt_i32 s89, 12
	s_cselect_b32 s14, 0xf0, s12
	s_add_i32 s14, s14, s92
	s_and_b64 s[20:21], s[8:9], exec
	s_cselect_b32 s14, s93, s14
	s_or_b32 s14, s14, 15
	v_sub_u32_e32 v2, s14, v45
	v_add_u32_e32 v67, s93, v45
	s_waitcnt vmcnt(15)
	v_cndmask_b32_e64 v68, v2, v67, s[8:9]
	s_waitcnt vmcnt(14)
	v_ashrrev_i32_e32 v69, 31, v68
	v_lshl_add_u64 v[68:69], s[16:17], 0, v[68:69]
	v_mad_u64_u32 v[112:113], s[20:21], v68, s43, v[24:25]
	v_mov_b32_e32 v2, v113
	v_mad_u64_u32 v[68:69], s[20:21], v69, s43, v[2:3]
	v_mov_b32_e32 v113, v68
	global_load_ushort v47, v[112:113], off
	s_and_b64 s[20:21], s[8:9], exec
	s_mov_b32 s20, 0xffff7600
	s_cselect_b32 s20, 0x8a00, s20
	s_cselect_b32 s21, 0, -1
	v_lshl_add_u64 v[112:113], v[112:113], 0, s[20:21]
	global_load_ushort v68, v[112:113], off
	v_lshl_add_u64 v[112:113], v[112:113], 0, s[20:21]
	global_load_ushort v69, v[112:113], off
	v_lshl_add_u64 v[112:113], v[112:113], 0, s[20:21]
	global_load_ushort v70, v[112:113], off

; #define LAS __attribute__((address_space(3)))
; __device__ __forceinline__ void scan_phase(const Params& P, int l, LAS unsigned char* lds) {
;     ...
;                         LAS unsigned char* sl = lds + (jw & 1) * SLOT;
; #pragma unroll
;                         for (int j = 0; j < 4; ++j) { *(LAS u32x4*)(sl + (j * 64 + lane) * 16) = fw[j]; *(LAS u32x4*)(sl + 4096 + (j * 64 + lane) * 16) = fq[j]; }
; #pragma unroll
;                         for (int m = 0; m < 8; ++m) *(LAS u32x2*)(sl + 8192 + (m * 64 + lane) * 8) = fk[m];
;                         *(LAS u32x2*)(sl + 12288 + lane * 8) = fa; *(LAS u32x2*)(sl + 12800 + lane * 8) = ft;
;                         *(LAS f32x4*)(sl + 13312 + lane * 16) = b4; *(LAS f32x4*)(sl + 14336 + lane * 16) = v4;
;                         if (lane == 0) *(LAS float*)(sl + 15360) = egC;
;                     }
;                     if (jl < NT) {
;                         const int n0 = jl * TS; const int plo = dir ? (n0 < 256 ? 256 - TS - n0 : TPB + 256 - TS - n0) : n0;
;                         const size_t task = (size_t)grp * NCHUNK + jl;
;                         const unsigned char* c1 = ws + WS_CP1 + task * CP1_STRIDE; const unsigned char* ck = ws + WS_CPK + task * 4096; const unsigned char* c2 = ws + WS_CP2 + task * CP2_STRIDE;
; #pragma unroll
;                         for (int j = 0; j < 4; ++j) { fw[j] = *(const u32x4*)(c1 + (size_t)(j * 64 + lane) * 16); fq[j] = *(const u32x4*)(c1 + 4096 + (size_t)(j * 64 + lane) * 16); }
; #pragma unroll
;                         for (int m = 0; m < 8; ++m) fk[m] = *(const u32x2*)(ck + (size_t)(m * 64 + lane) * 8);
;                         fa = *(const u32x2*)(c2 + (size_t)lane * 8); ft = *(const u32x2*)(c2 + 512 + (size_t)lane * 8);
;                         b4 = *(const f32x4*)(c2 + 1024 + quad * 16); egC = *(const float*)(c2 + 1024 + 64);
.LBB0_733:
	s_mul_hi_u32 s14, s73, 0xaaaaaaab
	s_lshr_b32 s14, s14, 1
	s_mul_i32 s14, s14, 3
	s_sub_i32 s15, s88, s14
	s_add_i32 s15, s82, s15
	s_cmp_lg_u32 s15, -4
	s_cbranch_scc1 .LBB0_740
	s_cmp_lt_i32 s82, -1
	s_cselect_b64 s[20:21], -1, 0
	s_cmpk_eq_i32 s89, 0x1130
	s_cselect_b64 s[22:23], -1, 0
	s_or_b64 s[20:21], s[20:21], s[22:23]
	s_and_b64 vcc, exec, s[20:21]
	s_cbranch_vccnz .LBB0_738
	s_andn2_b32 s15, 1, s82
	s_mulk_i32 s15, 0x6500
	s_add_i32 s15, s15, 0
	v_add_u32_e32 v0, s15, v46
	v_add_u32_e32 v1, s15, v48
	s_waitcnt vmcnt(0)
	ds_write_b128 v0, v[4:7]
	ds_write_b128 v0, v[12:15] offset:4096
	ds_write_b128 v0, v[16:19] offset:1024
	ds_write_b128 v0, v[24:27] offset:5120
	ds_write_b128 v0, v[20:23] offset:2048
	ds_write_b128 v0, v[28:31] offset:6144
	ds_write_b128 v0, v[8:11] offset:3072
	ds_write_b128 v0, v[32:35] offset:7168
	ds_write_b128 v0, v[156:159] offset:8192
	ds_write_b128 v0, v[160:163] offset:9216
	ds_write_b128 v0, v[164:167] offset:10240
	ds_write_b128 v0, v[168:171] offset:11264
	ds_write_b128 v0, v[172:175] offset:12288
	ds_write_b128 v0, v[36:39] offset:13312
	ds_write_b128 v0, v[40:43] offset:14336
	s_and_saveexec_b64 s[20:21], s[6:7]
	v_mov_b32_e32 v0, s15
	ds_write_b32 v0, v47 offset:15360
	s_or_b64 exec, exec, s[20:21]
.LBB0_738:
	s_cmpk_gt_i32 s82, 0x10b
	s_cbranch_scc1 .LBB0_740
	v_readlane_b32 s22, v252, 2
	v_readlane_b32 s23, v252, 3
	s_cmp_lt_i32 s82, 12
	s_cselect_b32 s15, 0xf0, s93
	v_lshl_add_u64 v[0:1], s[22:23], 0, v[68:69]
	s_waitcnt vmcnt(17)
	v_add_co_u32_e32 v8, vcc, 0x38b60000, v0
	s_add_i32 s15, s15, s83
	s_nop 0
	v_addc_co_u32_e32 v9, vcc, 0, v1, vcc
	v_add_co_u32_e32 v0, vcc, 0x38b61000, v0
	global_load_dwordx4 v[4:7], v[8:9], off
	s_nop 0
	v_addc_co_u32_e32 v1, vcc, 0, v1, vcc
	global_load_dwordx4 v[12:15], v[0:1], off
	global_load_dwordx4 v[16:19], v[8:9], off offset:1024
	global_load_dwordx4 v[24:27], v[0:1], off offset:1024
	global_load_dwordx4 v[20:23], v[8:9], off offset:2048
	global_load_dwordx4 v[28:31], v[0:1], off offset:2048
	s_nop 0
	global_load_dwordx4 v[8:11], v[8:9], off offset:3072
	s_nop 0
	global_load_dwordx4 v[32:35], v[0:1], off offset:3072
	v_lshl_add_u64 v[0:1], s[22:23], 0, v[66:67]
	v_add_co_u32_e32 v0, vcc, 0x17600000, v0
	s_and_b64 s[20:21], s[8:9], exec
	s_nop 0
	v_addc_co_u32_e32 v1, vcc, 0, v1, vcc
	v_add_co_u32_e32 v0, vcc, v48, v0
	s_nop 1
	v_addc_co_u32_e32 v1, vcc, 0, v1, vcc
	global_load_dwordx4 v[156:159], v[0:1], off
	global_load_dwordx4 v[160:163], v[0:1], off offset:1024
	global_load_dwordx4 v[164:167], v[0:1], off offset:2048
	global_load_dwordx4 v[168:171], v[0:1], off offset:3072
	v_lshl_add_u64 v[0:1], s[22:23], 0, v[64:65]
	s_mov_b32 s20, 0x413d0000
	v_add_co_u32_e32 v0, vcc, s20, v0
	s_cselect_b32 s15, s89, s15
	s_nop 0
	v_addc_co_u32_e32 v1, vcc, 0, v1, vcc
	s_add_u32 s20, s22, s80
	v_add_co_u32_e32 v0, vcc, v48, v0
	s_nop 1
	v_addc_co_u32_e32 v1, vcc, 0, v1, vcc
	global_load_dwordx4 v[172:175], v[0:1], off
	v_lshl_add_u64 v[0:1], s[22:23], 0, v[62:63]
	s_addc_u32 s21, s23, s81
	s_or_b32 s15, s15, 15
	global_load_dwordx4 v[36:39], v[0:1], off
	global_load_dword v47, v3, s[20:21]
	v_sub_u32_e32 v0, s15, v45
	v_add_u32_e32 v2, s89, v45
	v_cndmask_b32_e64 v0, v0, v2, s[8:9]
	v_ashrrev_i32_e32 v1, 31, v0
	v_lshl_add_u64 v[0:1], s[16:17], 0, v[0:1]
	v_lshlrev_b64 v[0:1], 12, v[0:1]
	v_lshl_add_u64 v[0:1], v[60:61], 0, v[0:1]
	global_load_dword v40, v[0:1], off
	s_and_b64 s[20:21], s[8:9], exec
	s_mov_b32 s20, 0xfffff000
	s_cselect_b32 s20, 0x1000, s20
	s_cselect_b32 s21, 0, -1
	v_lshl_add_u64 v[0:1], v[0:1], 0, s[20:21]
	global_load_dword v41, v[0:1], off
	v_lshl_add_u64 v[0:1], v[0:1], 0, s[20:21]
	global_load_dword v42, v[0:1], off
	v_lshl_add_u64 v[0:1], v[0:1], 0, s[20:21]
	global_load_dword v43, v[0:1], off
